# GDN scan loop duplicated for waves 2-3 with exact vmcnt counts (their 16 output stores per half-step no longer drained by the shared conservative waits); waves 0-1 unchanged
# baseline (speedup 1.0000x reference)
; #define SCAN_LOAD_A(AF, ci_) do { const bf16_t* ap_ = Abase + (size_t)(ci_) * 8192 + (mt * 8 * 64 + lane) * 8; \
;         _Pragma("unroll") for (int ks = 0; ks < 8; ++ks) AF[ks] = *(const bf16x8*)(ap_ + ks * 512); } while (0)
; #define SCAN_LOAD_K(ci_) do { const bf16_t* kp_ = Kbase + (size_t)(ci_) * 8192 + (wave * 4 * 64 + lane) * 8; \
;         _Pragma("unroll") for (int ks = 0; ks < 4; ++ks) Kf[ks] = *(const bf16x8*)(kp_ + ks * 512); } while (0)
; DI void gdn_scan(const Params& P, int item, unsigned char* smem, int tt) {
;     ...
;     const float glreg = glast[cb + (lane & 31)];
;     bf16x8 Af0[8], Af1[8], Kf[4];
;     u32x4 Xa, Xb, Xc, Xd;
;     Xc = Xd = (u32x4){0u, 0u, 0u, 0u};
;     SCAN_LOAD_A(Af0, cb); SCAN_LOAD_K(cb); SCAN_LOAD_X(cb);
;     SCAN_LOAD_A(Af1, cb + 1);
;     __syncthreads();
.LBB0_569:
	s_or_b64 exec, exec, s[30:31]
	global_load_dwordx4 v[122:125], v[18:19], off
	global_load_dwordx4 v[126:129], v[20:21], off
	v_or_b32_e32 v18, 1, v146
	v_ashrrev_i32_e32 v19, 31, v18
	v_lshlrev_b64 v[18:19], 14, v[18:19]
	v_lshl_add_u64 v[18:19], v[8:9], 0, v[18:19]
	v_mov_b32_e32 v13, v1
	v_lshl_add_u64 v[18:19], v[18:19], 0, v[12:13]
	global_load_dwordx4 v[74:77], v[18:19], off
	global_load_dwordx4 v[78:81], v[18:19], off offset:1024
	global_load_dwordx4 v[82:85], v[18:19], off offset:2048
	global_load_dwordx4 v[86:89], v[18:19], off offset:3072
	v_add_co_u32_e32 v18, vcc, s40, v18
	s_movk_i32 s30, 0x110
	s_nop 0
	v_addc_co_u32_e32 v19, vcc, 0, v19, vcc
	global_load_dwordx4 v[90:93], v[18:19], off
	global_load_dwordx4 v[94:97], v[18:19], off offset:1024
	global_load_dwordx4 v[98:101], v[18:19], off offset:2048
	global_load_dwordx4 v[102:105], v[18:19], off offset:3072
	v_mad_u32_u24 v19, v22, s30, v131
	s_movk_i32 s30, 0x90
	v_lshl_add_u64 v[148:149], v[8:9], 0, v[12:13]
	v_mad_u32_u24 v8, v22, s30, v131
	v_ashrrev_i32_e32 v18, 4, v3
	v_lshlrev_b32_e32 v21, 3, v23
	v_add_u32_e32 v0, v19, v2
	v_add_u32_e32 v147, v8, v2
	v_lshlrev_b32_e32 v2, 6, v26
	v_mov_b32_e32 v7, v1
	v_add3_u32 v171, v19, v2, v21
	v_ashrrev_i32_e32 v19, 31, v18
	v_lshl_add_u64 v[150:151], s[68:69], 0, v[6:7]
	v_lshlrev_b64 v[156:157], 21, v[18:19]
	v_lshlrev_b32_e32 v7, 9, v130
	s_mov_b32 s30, 0x8000
	v_lshlrev_b32_e32 v3, 6, v3
	v_add3_u32 v174, v8, v2, v21
	v_lshlrev_b32_e32 v2, 12, v23
	v_and_or_b32 v7, v7, s30, v156
	v_and_b32_e32 v3, 0x300, v3
	v_lshrrev_b32_e32 v20, 8, v24
	v_or3_b32 v2, v7, v2, v3
	v_lshlrev_b16_e32 v3, 1, v25
	v_add_u16_e32 v3, v3, v20
	v_and_b32_e32 v3, 3, v3
	v_lshlrev_b32_e32 v3, 6, v3
	v_lshlrev_b32_e32 v7, 1, v22
	v_lshlrev_b64 v[8:9], 1, v[16:17]
	v_lshlrev_b64 v[12:13], 1, v[14:15]
	v_or3_b32 v156, v2, v3, v7
	v_mov_b32_e32 v2, 0
	s_mov_b32 s39, 0
	v_or_b32_e32 v172, 2, v146
	v_or_b32_e32 v173, 3, v146
	v_lshl_add_u64 v[152:153], s[62:63], 0, v[8:9]
	v_lshl_add_u64 v[154:155], s[58:59], 0, v[12:13]
	v_lshl_add_u64 v[158:159], v[10:11], 0, v[8:9]
	v_or_b32_e32 v160, v4, v6
	v_mov_b32_e32 v161, v5
	v_lshl_add_u64 v[162:163], v[4:5], 0, v[12:13]
	v_mov_b32_e32 v3, v2
	v_mov_b32_e32 v4, v2
	v_mov_b32_e32 v5, v2
	v_mov_b32_e32 v6, v2
	v_mov_b32_e32 v7, v2
	v_mov_b32_e32 v8, v2
	v_mov_b32_e32 v9, v2
	v_mov_b32_e32 v10, v2
	v_mov_b32_e32 v11, v2
	v_mov_b32_e32 v12, v2
	v_mov_b32_e32 v13, v2
	v_mov_b32_e32 v14, v2
	v_mov_b32_e32 v15, v2
	v_mov_b32_e32 v16, v2
	v_mov_b32_e32 v17, v2
	s_waitcnt lgkmcnt(0)
	s_barrier
	s_cmp_lg_u64 s[2:3], 0
	s_cbranch_scc1 .Lscan23_entry
	s_branch .LBB0_571

; DI void gdn_scan(const Params& P, int item, unsigned char* smem, int tt) {
;     ...
; #pragma unroll 1
;     for (int n = 0; n < 32; n += 2) {
;         SCAN_STEP(Af0, n);
;         SCAN_STEP(Af1, n + 1);
;     }
.Lscan23_entry:
	s_waitcnt vmcnt(0)
	s_branch .Lscan23_571

.Lscan23_571:
	ds_read_b128 v[18:21], v0
	ds_read_b128 v[130:133], v0 offset:32
	ds_read_b128 v[134:137], v0 offset:64
	ds_read_b128 v[138:141], v0 offset:96
	ds_read_b128 v[142:145], v0 offset:128
	ds_read_b128 v[176:179], v0 offset:160
	ds_read_b128 v[180:183], v0 offset:192
	ds_read_b128 v[184:187], v0 offset:224
	s_add_i32 s38, s39, 2
	s_cmp_gt_u32 s39, 29
	s_cselect_b64 s[30:31], -1, 0
	s_cmp_lt_u32 s39, 30
	s_cselect_b32 s34, s38, 31
	v_add_u32_e32 v164, s34, v146
	s_waitcnt vmcnt(56) lgkmcnt(7)
	v_mfma_f32_32x32x16_bf16 v[18:33], v[34:37], v[18:21], 0
	s_waitcnt vmcnt(56) lgkmcnt(6)
	v_mfma_f32_32x32x16_bf16 v[18:33], v[38:41], v[130:133], v[18:33]
	s_waitcnt vmcnt(56) lgkmcnt(5)
	v_mfma_f32_32x32x16_bf16 v[18:33], v[42:45], v[134:137], v[18:33]
	s_waitcnt vmcnt(56) lgkmcnt(4)
	v_mfma_f32_32x32x16_bf16 v[18:33], v[46:49], v[138:141], v[18:33]
	s_waitcnt vmcnt(56) lgkmcnt(3)
	v_mfma_f32_32x32x16_bf16 v[18:33], v[50:53], v[142:145], v[18:33]
	s_waitcnt vmcnt(56) lgkmcnt(2)
	v_mfma_f32_32x32x16_bf16 v[18:33], v[54:57], v[176:179], v[18:33]
	s_waitcnt vmcnt(56) lgkmcnt(1)
	v_mfma_f32_32x32x16_bf16 v[18:33], v[58:61], v[180:183], v[18:33]
	s_waitcnt vmcnt(56) lgkmcnt(0)
	v_mfma_f32_32x32x16_bf16 v[18:33], v[62:65], v[184:187], v[18:33]
	v_ashrrev_i32_e32 v165, 31, v164
	v_lshlrev_b64 v[34:35], 14, v[164:165]
	v_lshl_add_u64 v[50:51], v[148:149], 0, v[34:35]
	v_add_co_u32_e32 v62, vcc, 0x1000, v50
	global_load_dwordx4 v[34:37], v[50:51], off
	global_load_dwordx4 v[38:41], v[50:51], off offset:1024
	global_load_dwordx4 v[42:45], v[50:51], off offset:2048
	global_load_dwordx4 v[46:49], v[50:51], off offset:3072
	v_addc_co_u32_e32 v63, vcc, 0, v51, vcc
	global_load_dwordx4 v[50:53], v[62:63], off
	global_load_dwordx4 v[54:57], v[62:63], off offset:1024
	global_load_dwordx4 v[58:61], v[62:63], off offset:2048
	s_nop 0
	global_load_dwordx4 v[62:65], v[62:63], off offset:3072
	v_readlane_b32 s34, v170, s39
	v_add_u32_e32 v175, 0x2000, v174
	s_and_saveexec_b64 s[36:37], s[0:1]
	s_cbranch_execz .Lscan23_573
	s_waitcnt vmcnt(9)
	v_lshlrev_b32_e32 v130, 16, v122
	v_and_b32_e32 v131, 0xffff0000, v122
	v_lshlrev_b32_e32 v132, 16, v123
	v_and_b32_e32 v133, 0xffff0000, v123
	v_pk_add_f32 v[130:131], v[130:131], v[18:19] neg_lo:[0,1] neg_hi:[0,1]
	v_pk_add_f32 v[132:133], v[132:133], v[20:21] neg_lo:[0,1] neg_hi:[0,1]
	v_cvt_pk_bf16_f32 v130, v130, v131
	v_cvt_pk_bf16_f32 v131, v132, v133
	v_lshlrev_b32_e32 v132, 16, v124
	v_and_b32_e32 v133, 0xffff0000, v124
	v_lshlrev_b32_e32 v134, 16, v125
	v_and_b32_e32 v135, 0xffff0000, v125
	v_pk_add_f32 v[132:133], v[132:133], v[22:23] neg_lo:[0,1] neg_hi:[0,1]
	v_pk_add_f32 v[134:135], v[134:135], v[24:25] neg_lo:[0,1] neg_hi:[0,1]
	v_cvt_pk_bf16_f32 v132, v132, v133
	v_cvt_pk_bf16_f32 v133, v134, v135
	ds_write2_b64 v175, v[130:131], v[132:133] offset0:64 offset1:66
	s_waitcnt vmcnt(8)
	v_lshlrev_b32_e32 v130, 16, v126
	v_and_b32_e32 v131, 0xffff0000, v126
	v_lshlrev_b32_e32 v132, 16, v127
	v_and_b32_e32 v133, 0xffff0000, v127
	v_pk_add_f32 v[130:131], v[130:131], v[26:27] neg_lo:[0,1] neg_hi:[0,1]
	v_pk_add_f32 v[132:133], v[132:133], v[28:29] neg_lo:[0,1] neg_hi:[0,1]
	v_cvt_pk_bf16_f32 v130, v130, v131
	v_cvt_pk_bf16_f32 v131, v132, v133
	v_lshlrev_b32_e32 v132, 16, v128
	v_and_b32_e32 v133, 0xffff0000, v128
	v_lshlrev_b32_e32 v134, 16, v129
	v_and_b32_e32 v135, 0xffff0000, v129
	v_pk_add_f32 v[132:133], v[132:133], v[30:31] neg_lo:[0,1] neg_hi:[0,1]
	v_pk_add_f32 v[134:135], v[134:135], v[32:33] neg_lo:[0,1] neg_hi:[0,1]
	v_cvt_pk_bf16_f32 v132, v132, v133
	v_cvt_pk_bf16_f32 v133, v134, v135
	ds_write2_b64 v175, v[130:131], v[132:133] offset0:68 offset1:70
.Lscan23_573:
	s_or_b64 exec, exec, s[36:37]
	s_waitcnt lgkmcnt(0)
	s_barrier
	ds_read_b128 v[142:145], v147 offset:8704
	ds_read_b128 v[138:141], v147 offset:8736
	ds_read_b128 v[134:137], v147 offset:8768
	ds_read_b128 v[130:133], v147 offset:8800
	v_pk_mul_f32 v[16:17], v[16:17], s[34:35] op_sel_hi:[1,0]
	v_pk_mul_f32 v[14:15], v[14:15], s[34:35] op_sel_hi:[1,0]
	v_pk_mul_f32 v[12:13], v[12:13], s[34:35] op_sel_hi:[1,0]
	v_pk_mul_f32 v[10:11], v[10:11], s[34:35] op_sel_hi:[1,0]
	v_pk_mul_f32 v[8:9], v[8:9], s[34:35] op_sel_hi:[1,0]
	v_pk_mul_f32 v[6:7], v[6:7], s[34:35] op_sel_hi:[1,0]
	v_pk_mul_f32 v[4:5], v[4:5], s[34:35] op_sel_hi:[1,0]
	v_pk_mul_f32 v[2:3], v[2:3], s[34:35] op_sel_hi:[1,0]
	s_waitcnt vmcnt(31) lgkmcnt(3)
	s_nop 0
	v_mfma_f32_32x32x16_bf16 v[2:17], v[118:121], v[142:145], v[2:17]
	s_waitcnt vmcnt(30) lgkmcnt(2)
	v_mfma_f32_32x32x16_bf16 v[2:17], v[114:117], v[138:141], v[2:17]
	s_waitcnt vmcnt(29) lgkmcnt(1)
	v_mfma_f32_32x32x16_bf16 v[2:17], v[110:113], v[134:137], v[2:17]
	s_waitcnt vmcnt(28) lgkmcnt(0)
	v_mfma_f32_32x32x16_bf16 v[2:17], v[106:109], v[130:133], v[2:17]
	s_and_saveexec_b64 s[34:35], s[2:3]
	s_cbranch_execz .Lscan23_575
	s_waitcnt vmcnt(25)
	v_mfma_f32_32x32x16_bf16 v[18:33], v[122:125], v[142:145], v[18:33]
	s_waitcnt vmcnt(24)
	v_mfma_f32_32x32x16_bf16 v[18:33], v[126:129], v[138:141], v[18:33]
	v_mfma_f32_32x32x16_bf16 v[18:33], v[70:73], v[134:137], v[18:33]
	v_mfma_f32_32x32x16_bf16 v[18:33], v[66:69], v[130:133], v[18:33]
.Lscan23_575:
	s_or_b64 exec, exec, s[34:35]
	v_lshl_add_u64 v[106:107], s[80:81], 0, v[160:161]
	v_add_co_u32_e32 v106, vcc, 0xc004000, v106
	s_nop 1
	v_addc_co_u32_e32 v107, vcc, 0, v107, vcc
	global_load_dwordx4 v[118:121], v[106:107], off
	global_load_dwordx4 v[114:117], v[106:107], off offset:1024
	global_load_dwordx4 v[110:113], v[106:107], off offset:2048
	s_nop 0
	global_load_dwordx4 v[106:109], v[106:107], off offset:3072
	s_and_saveexec_b64 s[34:35], s[2:3]
	s_xor_b64 s[34:35], exec, s[34:35]
	s_cbranch_execz .Lscan23_577
	v_lshl_add_u64 v[66:67], s[80:81], 0, v[158:159]
	v_add_co_u32_e32 v66, vcc, 0xd002000, v66
	s_waitcnt vmcnt(28)
	v_add3_u32 v122, v146, s39, 1
	v_addc_co_u32_e32 v67, vcc, 0, v67, vcc
	global_load_dwordx4 v[70:73], v[66:67], off offset:2048
	s_nop 0
	global_load_dwordx4 v[66:69], v[66:67], off offset:3072
	v_ashrrev_i32_e32 v123, 31, v122
	v_lshlrev_b64 v[122:123], 13, v[122:123]
	v_lshl_add_u64 v[122:123], v[152:153], 0, v[122:123]
	v_lshl_add_u64 v[124:125], v[122:123], 0, s[20:21]

.Lscan23_579:
	s_or_b64 exec, exec, s[34:35]
	s_waitcnt vmcnt(30)
	global_load_dwordx4 v[126:129], v[122:123], off
	s_nop 0
	global_load_dwordx4 v[122:125], v[124:125], off
	v_cvt_pk_bf16_f32 v130, v2, v3
	v_cvt_pk_bf16_f32 v131, v4, v5
	v_cvt_pk_bf16_f32 v132, v6, v7
	v_cvt_pk_bf16_f32 v133, v8, v9
	ds_write2_b64 v171, v[130:131], v[132:133] offset1:2
	v_cvt_pk_bf16_f32 v130, v10, v11
	v_cvt_pk_bf16_f32 v131, v12, v13
	v_cvt_pk_bf16_f32 v132, v14, v15
	v_cvt_pk_bf16_f32 v133, v16, v17
	v_lshl_add_u64 v[164:165], s[80:81], 0, v[156:157]
	ds_write2_b64 v171, v[130:131], v[132:133] offset0:4 offset1:6
	s_and_saveexec_b64 s[34:35], s[2:3]
	s_cbranch_execz .Lscan23_581
	v_add_co_u32_e32 v130, vcc, 0x2000000, v164
	v_cvt_pk_bf16_f32 v18, v18, s0
	s_nop 0
	v_addc_co_u32_e32 v131, vcc, 0, v165, vcc
	global_store_short v[130:131], v18, off
	v_cvt_pk_bf16_f32 v18, v19, s0
	global_store_short v[130:131], v18, off offset:1024
	v_cvt_pk_bf16_f32 v18, v20, s0
	global_store_short v[130:131], v18, off offset:2048
	v_cvt_pk_bf16_f32 v18, v21, s0
	global_store_short v[130:131], v18, off offset:3072
	v_add_co_u32_e32 v18, vcc, s41, v164
	v_cvt_pk_bf16_f32 v20, v22, s0
	s_nop 0
	v_addc_co_u32_e32 v19, vcc, 0, v165, vcc
	global_store_short v[18:19], v20, off
	v_cvt_pk_bf16_f32 v20, v23, s0
	global_store_short v[18:19], v20, off offset:1024
	v_cvt_pk_bf16_f32 v20, v24, s0
	global_store_short v[18:19], v20, off offset:2048
	v_cvt_pk_bf16_f32 v20, v25, s0
	global_store_short v[18:19], v20, off offset:3072
	v_add_co_u32_e32 v18, vcc, s42, v164
	v_cvt_pk_bf16_f32 v20, v26, s0
	s_nop 0
	v_addc_co_u32_e32 v19, vcc, 0, v165, vcc
	global_store_short v[18:19], v20, off
	v_cvt_pk_bf16_f32 v20, v27, s0
	global_store_short v[18:19], v20, off offset:1024
	v_cvt_pk_bf16_f32 v20, v28, s0
	global_store_short v[18:19], v20, off offset:2048
	v_cvt_pk_bf16_f32 v20, v29, s0
	global_store_short v[18:19], v20, off offset:3072
	v_add_co_u32_e32 v18, vcc, 0x2006000, v164
	v_cvt_pk_bf16_f32 v20, v30, s0
	s_nop 0
	v_addc_co_u32_e32 v19, vcc, 0, v165, vcc
	global_store_short v[18:19], v20, off
	v_cvt_pk_bf16_f32 v20, v31, s0
	global_store_short v[18:19], v20, off offset:1024
	v_cvt_pk_bf16_f32 v20, v32, s0
	global_store_short v[18:19], v20, off offset:2048
	v_cvt_pk_bf16_f32 v20, v33, s0
	global_store_short v[18:19], v20, off offset:3072
.Lscan23_581:
	s_or_b64 exec, exec, s[34:35]
	s_waitcnt lgkmcnt(0)
	s_barrier
	ds_read_b128 v[18:21], v0
	ds_read_b128 v[130:133], v0 offset:32
	ds_read_b128 v[134:137], v0 offset:64
	ds_read_b128 v[138:141], v0 offset:96
	ds_read_b128 v[142:145], v0 offset:128
	ds_read_b128 v[176:179], v0 offset:160
	ds_read_b128 v[180:183], v0 offset:192
	ds_read_b128 v[184:187], v0 offset:224
	s_add_i32 s34, s39, 1
	s_min_u32 s35, s39, 28
	v_add_u32_e32 v188, s35, v173
	s_waitcnt vmcnt(56) lgkmcnt(7)
	v_mfma_f32_32x32x16_bf16 v[18:33], v[74:77], v[18:21], 0
	s_waitcnt vmcnt(56) lgkmcnt(6)
	v_mfma_f32_32x32x16_bf16 v[18:33], v[78:81], v[130:133], v[18:33]
	s_waitcnt vmcnt(56) lgkmcnt(5)
	v_mfma_f32_32x32x16_bf16 v[18:33], v[82:85], v[134:137], v[18:33]
	s_waitcnt vmcnt(56) lgkmcnt(4)
	v_mfma_f32_32x32x16_bf16 v[18:33], v[86:89], v[138:141], v[18:33]
	s_waitcnt vmcnt(56) lgkmcnt(3)
	v_mfma_f32_32x32x16_bf16 v[18:33], v[90:93], v[142:145], v[18:33]
	s_waitcnt vmcnt(56) lgkmcnt(2)
	v_mfma_f32_32x32x16_bf16 v[18:33], v[94:97], v[176:179], v[18:33]
	s_waitcnt vmcnt(56) lgkmcnt(1)
	v_mfma_f32_32x32x16_bf16 v[18:33], v[98:101], v[180:183], v[18:33]
	s_waitcnt vmcnt(56) lgkmcnt(0)
	v_mfma_f32_32x32x16_bf16 v[18:33], v[102:105], v[184:187], v[18:33]
	v_ashrrev_i32_e32 v189, 31, v188
	v_lshlrev_b64 v[74:75], 14, v[188:189]
	v_lshl_add_u64 v[90:91], v[148:149], 0, v[74:75]
	v_add_co_u32_e32 v102, vcc, 0x1000, v90
	global_load_dwordx4 v[74:77], v[90:91], off
	global_load_dwordx4 v[78:81], v[90:91], off offset:1024
	global_load_dwordx4 v[82:85], v[90:91], off offset:2048
	global_load_dwordx4 v[86:89], v[90:91], off offset:3072
	v_addc_co_u32_e32 v103, vcc, 0, v91, vcc
	global_load_dwordx4 v[90:93], v[102:103], off
	global_load_dwordx4 v[94:97], v[102:103], off offset:1024
	global_load_dwordx4 v[98:101], v[102:103], off offset:2048
	s_nop 0
	global_load_dwordx4 v[102:105], v[102:103], off offset:3072
	v_readlane_b32 s34, v170, s34
	s_and_saveexec_b64 s[36:37], s[0:1]
	s_cbranch_execz .Lscan23_583
	s_waitcnt vmcnt(9)
	v_lshlrev_b32_e32 v130, 16, v126
	v_and_b32_e32 v131, 0xffff0000, v126
	v_lshlrev_b32_e32 v132, 16, v127
	v_and_b32_e32 v133, 0xffff0000, v127
	v_pk_add_f32 v[130:131], v[130:131], v[18:19] neg_lo:[0,1] neg_hi:[0,1]
	v_pk_add_f32 v[132:133], v[132:133], v[20:21] neg_lo:[0,1] neg_hi:[0,1]
	v_cvt_pk_bf16_f32 v130, v130, v131
	v_cvt_pk_bf16_f32 v131, v132, v133
	v_lshlrev_b32_e32 v132, 16, v128
	v_and_b32_e32 v133, 0xffff0000, v128
	v_lshlrev_b32_e32 v134, 16, v129
	v_and_b32_e32 v135, 0xffff0000, v129
	v_pk_add_f32 v[132:133], v[132:133], v[22:23] neg_lo:[0,1] neg_hi:[0,1]
	v_pk_add_f32 v[134:135], v[134:135], v[24:25] neg_lo:[0,1] neg_hi:[0,1]
	v_cvt_pk_bf16_f32 v132, v132, v133
	v_cvt_pk_bf16_f32 v133, v134, v135
	ds_write2_b64 v175, v[130:131], v[132:133] offset0:64 offset1:66
	s_waitcnt vmcnt(8)
	v_lshlrev_b32_e32 v130, 16, v122
	v_and_b32_e32 v131, 0xffff0000, v122
	v_lshlrev_b32_e32 v132, 16, v123
	v_and_b32_e32 v133, 0xffff0000, v123
	v_pk_add_f32 v[130:131], v[130:131], v[26:27] neg_lo:[0,1] neg_hi:[0,1]
	v_pk_add_f32 v[132:133], v[132:133], v[28:29] neg_lo:[0,1] neg_hi:[0,1]
	v_cvt_pk_bf16_f32 v130, v130, v131
	v_cvt_pk_bf16_f32 v131, v132, v133
	v_lshlrev_b32_e32 v132, 16, v124
	v_and_b32_e32 v133, 0xffff0000, v124
	v_lshlrev_b32_e32 v134, 16, v125
	v_and_b32_e32 v135, 0xffff0000, v125
	v_pk_add_f32 v[132:133], v[132:133], v[30:31] neg_lo:[0,1] neg_hi:[0,1]
	v_pk_add_f32 v[134:135], v[134:135], v[32:33] neg_lo:[0,1] neg_hi:[0,1]
	v_cvt_pk_bf16_f32 v132, v132, v133
	v_cvt_pk_bf16_f32 v133, v134, v135
	ds_write2_b64 v175, v[130:131], v[132:133] offset0:68 offset1:70
.Lscan23_583:
	s_or_b64 exec, exec, s[36:37]
	s_waitcnt lgkmcnt(0)
	s_barrier
	ds_read_b128 v[142:145], v147 offset:8704
	ds_read_b128 v[138:141], v147 offset:8736
	ds_read_b128 v[134:137], v147 offset:8768
	ds_read_b128 v[130:133], v147 offset:8800
	v_pk_mul_f32 v[16:17], v[16:17], s[34:35] op_sel_hi:[1,0]
	v_pk_mul_f32 v[14:15], v[14:15], s[34:35] op_sel_hi:[1,0]
	v_pk_mul_f32 v[12:13], v[12:13], s[34:35] op_sel_hi:[1,0]
	v_pk_mul_f32 v[10:11], v[10:11], s[34:35] op_sel_hi:[1,0]
	v_pk_mul_f32 v[8:9], v[8:9], s[34:35] op_sel_hi:[1,0]
	v_pk_mul_f32 v[6:7], v[6:7], s[34:35] op_sel_hi:[1,0]
	v_pk_mul_f32 v[4:5], v[4:5], s[34:35] op_sel_hi:[1,0]
	v_pk_mul_f32 v[2:3], v[2:3], s[34:35] op_sel_hi:[1,0]
	s_waitcnt vmcnt(31) lgkmcnt(3)
	s_nop 0
	v_mfma_f32_32x32x16_bf16 v[2:17], v[118:121], v[142:145], v[2:17]
	s_waitcnt vmcnt(30) lgkmcnt(2)
	v_mfma_f32_32x32x16_bf16 v[2:17], v[114:117], v[138:141], v[2:17]
	s_waitcnt vmcnt(29) lgkmcnt(1)
	v_mfma_f32_32x32x16_bf16 v[2:17], v[110:113], v[134:137], v[2:17]
	s_waitcnt vmcnt(28) lgkmcnt(0)
	v_mfma_f32_32x32x16_bf16 v[2:17], v[106:109], v[130:133], v[2:17]
	s_and_saveexec_b64 s[34:35], s[2:3]
	s_cbranch_execz .Lscan23_585
	s_waitcnt vmcnt(25)
	v_mfma_f32_32x32x16_bf16 v[18:33], v[126:129], v[142:145], v[18:33]
	s_waitcnt vmcnt(24)
	v_mfma_f32_32x32x16_bf16 v[18:33], v[122:125], v[138:141], v[18:33]
	v_mfma_f32_32x32x16_bf16 v[18:33], v[70:73], v[134:137], v[18:33]
	v_mfma_f32_32x32x16_bf16 v[18:33], v[66:69], v[130:133], v[18:33]
.Lscan23_585:
	s_or_b64 exec, exec, s[34:35]
	s_min_u32 s34, s39, 29
	s_waitcnt vmcnt(24)
	v_add_u32_e32 v122, s34, v172
	v_ashrrev_i32_e32 v123, 31, v122
	v_lshlrev_b64 v[106:107], 14, v[122:123]
	v_lshl_add_u64 v[106:107], v[150:151], 0, v[106:107]
	global_load_dwordx4 v[118:121], v[106:107], off
	global_load_dwordx4 v[114:117], v[106:107], off offset:1024
	global_load_dwordx4 v[110:113], v[106:107], off offset:2048
	s_nop 0
	global_load_dwordx4 v[106:109], v[106:107], off offset:3072
	v_lshlrev_b64 v[124:125], 13, v[122:123]
	s_and_saveexec_b64 s[34:35], s[2:3]
	s_xor_b64 s[34:35], exec, s[34:35]
	s_cbranch_execz .Lscan23_587
	v_lshl_add_u64 v[122:123], v[152:153], 0, v[124:125]
	global_load_dwordx4 v[70:73], v[122:123], off offset:2048
	global_load_dwordx4 v[66:69], v[122:123], off offset:3072
	v_lshl_add_u64 v[126:127], v[122:123], 0, s[20:21]
